# GEMM unit start: first K iteration peeled, first MFMA of each accumulator takes SrcC=0, the 128 accumulator-zeroing v_mov per unit deleted (on top of v022 pitch288)
# speedup vs baseline: 1.0378x; 1.0014x over previous
; #define PG8_STAGE(bufoff, gbase, voff) do { _Pragma("unroll") for (int _i = 0; _i < 2; ++_i) \
;         __builtin_amdgcn_global_load_lds((const unsigned*)((const char*)(gbase) + (voff)[_i]), (LAS unsigned*)(lds + (bufoff) + ldsw + _i * 8192), 16, 0, 0); } while (0)
; #define PG8_LDA(dst, b, h) do { _Pragma("unroll") for (int m = 0; m < 4; ++m) _Pragma("unroll") for (int k = 0; k < 2; ++k) dst[m][k] = *(const LAS bf16x8*)(lds + PG8_SA(b, h) + aoff + m * 2048 + k * 1024); } while (0)
; #define PG8_LDB(dst, b, h) do { _Pragma("unroll") for (int n = 0; n < 2; ++n) _Pragma("unroll") for (int k = 0; k < 2; ++k) dst[n][k] = *(const LAS bf16x8*)(lds + PG8_SB(b, h) + boff + n * 2048 + k * 1024); } while (0)
; #define PG8_WAIT_V(n) asm volatile("s_waitcnt vmcnt(" #n ")" ::: "memory")
; #define PG8_WAIT_L(n) asm volatile("s_waitcnt lgkmcnt(" #n ")" ::: "memory")
; #define PG8_BAR __builtin_amdgcn_s_barrier()
; #define PG8_SCHED __builtin_amdgcn_sched_barrier(0)
; __device__ __forceinline__ void gemm_phase(const int tid, LAS unsigned char* lds, const Gemm g, const StaticOrder& S, const int mode  , void* Cout, const int ldc, float* rvs, const float* rbs, const float* rbs_tail) {
;     ...
;         for (int t = 0; t < ntu; t += 2) {
;             const bool last = (t == ntu - 2);
;             const char* a1 = cA + (size_t)(t + 1) * kstep;
;             const char* a2 = last ? nA : cA + (size_t)(t + 2) * kstep; const char* b2 = last ? nB : cB + (size_t)(t + 2) * kstep;
;             const char* a3 = a2 + kstep; const char* b3 = b2 + kstep;
;             PG8_LDB(B0, 0, 0); PG8_LDB(B1, 0, 1); PG8_SCHED; PG8_LDA(At, 0, 0); PG8_STAGE(PG8_SA(1, 1), a1 + hstepA, voffA);
;             PG8_WAIT_V(8); PG8_WAIT_L(0); PG8_BAR; PG8_MMA(0, 0, At, B0); PG8_MMA(0, 1, At, B1); PG8_BAR; PG8_SCHED;
;             PG8_LDA(At, 0, 1); PG8_STAGE(PG8_SB(0, 0), b2, voffB); PG8_STAGE(PG8_SB(0, 1), b2 + hstepB, voffB); PG8_STAGE(PG8_SA(0, 0), a2, voffA);
;             PG8_WAIT_V(8); PG8_WAIT_L(0); PG8_BAR; PG8_MMA(1, 0, At, B0); PG8_MMA(1, 1, At, B1); PG8_BAR; PG8_SCHED;
;     ...
; #pragma unroll
;         for (int a = 0; a < 2; ++a)
; #pragma unroll
;             for (int b = 0; b < 2; ++b)
; #pragma unroll
;                 for (int m = 0; m < 4; ++m)
; #pragma unroll
;                     for (int n = 0; n < 2; ++n) acc[a][b][m][n] = (f32x4){0.f, 0.f, 0.f, 0.f};
.LBB0_230:
	s_cmp_lt_i32 s44, 0
	s_cselect_b64 s[24:25], -1, 0
	s_and_b64 s[72:73], s[24:25], exec
	s_cselect_b32 s3, s48, 8
	s_add_i32 s33, s3, -2
	s_add_u32 s60, s60, 0x80
	s_addc_u32 s61, s61, 0
	s_add_u32 s45, s62, 0x100
	s_mov_b32 s68, 0
	s_addc_u32 s53, s63, 0
	s_waitcnt vmcnt(0)
	s_waitcnt lgkmcnt(0)
.Lgemm_peel:
	s_add_i32 s72, s68, 2
	s_add_u32 s62, s60, 0x80
	s_addc_u32 s63, s61, 0
	s_add_i32 s73, 0, 0x10000
	s_cmp_eq_u32 s33, s68
	s_cselect_b32 s63, s55, s63
	s_cselect_b32 s62, s54, s62
	v_add_u32_e32 v158, s73, v147
	s_cselect_b32 s75, s57, s53
	s_cselect_b32 s74, s56, s45
	s_add_i32 s68, 0, 0x14000
	ds_read_b128 v[142:145], v158
	ds_read_b128 v[150:153], v158 offset:1024
	ds_read_b128 v[154:157], v158 offset:2048
	ds_read_b128 v[168:171], v158 offset:3072
	v_add_u32_e32 v158, s68, v147
	ds_read_b128 v[172:175], v158
	ds_read_b128 v[176:179], v158 offset:1024
	ds_read_b128 v[180:183], v158 offset:2048
	ds_read_b128 v[184:187], v158 offset:3072
	v_lshl_add_u64 v[158:159], s[60:61], 0, v[138:139]
	s_add_i32 m0, s71, 0xc000
	ds_read_b128 v[188:191], v149
	ds_read_b128 v[212:215], v149 offset:1024
	ds_read_b128 v[216:219], v149 offset:2048
	ds_read_b128 v[220:223], v149 offset:3072
	ds_read_b128 v[224:227], v149 offset:4096
	ds_read_b128 v[228:231], v149 offset:5120
	ds_read_b128 v[232:235], v149 offset:6144
	ds_read_b128 v[236:239], v149 offset:7168
	global_load_lds_dwordx4 v[158:159], off
	v_lshl_add_u64 v[158:159], s[60:61], 0, v[140:141]
	s_add_i32 m0, s71, 0xe000
	s_nop 0
	global_load_lds_dwordx4 v[158:159], off
	s_waitcnt vmcnt(8)
	s_waitcnt lgkmcnt(0)
	s_barrier
	s_setprio 1
	s_waitcnt lgkmcnt(0)
	v_mfma_f32_16x16x32_bf16 v[124:127], v[142:145], v[188:191], 0
	v_mfma_f32_16x16x32_bf16 v[120:123], v[154:157], v[188:191], 0
	v_mfma_f32_16x16x32_bf16 v[116:119], v[142:145], v[216:219], 0
	v_mfma_f32_16x16x32_bf16 v[112:115], v[154:157], v[216:219], 0
	v_mfma_f32_16x16x32_bf16 v[104:107], v[142:145], v[224:227], 0
	v_mfma_f32_16x16x32_bf16 v[96:99], v[154:157], v[224:227], 0
	v_mfma_f32_16x16x32_bf16 v[88:91], v[142:145], v[232:235], 0
	v_mfma_f32_16x16x32_bf16 v[80:83], v[154:157], v[232:235], 0
	v_mfma_f32_16x16x32_bf16 v[124:127], v[150:153], v[212:215], v[124:127]
	v_mfma_f32_16x16x32_bf16 v[120:123], v[168:171], v[212:215], v[120:123]
	v_mfma_f32_16x16x32_bf16 v[116:119], v[150:153], v[220:223], v[116:119]
	v_mfma_f32_16x16x32_bf16 v[112:115], v[168:171], v[220:223], v[112:115]
	v_mfma_f32_16x16x32_bf16 v[104:107], v[150:153], v[228:231], v[104:107]
	v_mfma_f32_16x16x32_bf16 v[96:99], v[168:171], v[228:231], v[96:99]
	v_mfma_f32_16x16x32_bf16 v[88:91], v[150:153], v[236:239], v[88:91]
	v_mfma_f32_16x16x32_bf16 v[80:83], v[168:171], v[236:239], v[80:83]
	s_setprio 0
	s_setprio 1
	v_mfma_f32_16x16x32_bf16 v[108:111], v[172:175], v[188:191], 0
	v_mfma_f32_16x16x32_bf16 v[100:103], v[180:183], v[188:191], 0
	v_mfma_f32_16x16x32_bf16 v[92:95], v[172:175], v[216:219], 0
	v_mfma_f32_16x16x32_bf16 v[84:87], v[180:183], v[216:219], 0
	v_mfma_f32_16x16x32_bf16 v[76:79], v[172:175], v[224:227], 0
	v_mfma_f32_16x16x32_bf16 v[72:75], v[180:183], v[224:227], 0
	v_mfma_f32_16x16x32_bf16 v[68:71], v[172:175], v[232:235], 0
	v_mfma_f32_16x16x32_bf16 v[64:67], v[180:183], v[232:235], 0
	v_mfma_f32_16x16x32_bf16 v[108:111], v[176:179], v[212:215], v[108:111]
	v_mfma_f32_16x16x32_bf16 v[100:103], v[184:187], v[212:215], v[100:103]
	v_mfma_f32_16x16x32_bf16 v[92:95], v[176:179], v[220:223], v[92:95]
	v_mfma_f32_16x16x32_bf16 v[84:87], v[184:187], v[220:223], v[84:87]
	v_mfma_f32_16x16x32_bf16 v[76:79], v[176:179], v[228:231], v[76:79]
	v_mfma_f32_16x16x32_bf16 v[72:75], v[184:187], v[228:231], v[72:75]
	v_mfma_f32_16x16x32_bf16 v[68:71], v[176:179], v[236:239], v[68:71]
	v_mfma_f32_16x16x32_bf16 v[64:67], v[184:187], v[236:239], v[64:67]
	s_setprio 0
	s_barrier
	s_add_i32 s73, s73, s70
	v_lshl_add_u64 v[158:159], s[74:75], 0, v[160:161]
	s_mov_b32 m0, s73
	ds_read_b128 v[188:191], v149 offset:16384
	ds_read_b128 v[212:215], v149 offset:17408
	ds_read_b128 v[216:219], v149 offset:18432
	ds_read_b128 v[220:223], v149 offset:19456
	ds_read_b128 v[224:227], v149 offset:20480
	ds_read_b128 v[228:231], v149 offset:21504
	ds_read_b128 v[232:235], v149 offset:22528
	ds_read_b128 v[236:239], v149 offset:23552
	global_load_lds_dwordx4 v[158:159], off
	s_add_i32 m0, s73, 0x2000
	v_lshl_add_u64 v[192:193], s[74:75], 0, v[132:133]
	s_add_u32 s74, s74, s59
	s_addc_u32 s75, s75, 0
	s_add_i32 s68, s68, s70
	global_load_lds_dwordx4 v[192:193], off
	v_lshl_add_u64 v[194:195], s[74:75], 0, v[160:161]
	s_mov_b32 m0, s68
	v_lshl_add_u64 v[240:241], s[74:75], 0, v[132:133]
	global_load_lds_dwordx4 v[194:195], off
	s_add_i32 m0, s68, 0x2000
	v_lshl_add_u64 v[242:243], s[62:63], 0, v[128:129]
	global_load_lds_dwordx4 v[240:241], off
	s_mov_b32 m0, s71
	v_lshl_add_u64 v[244:245], s[62:63], 0, v[130:131]
	global_load_lds_dwordx4 v[242:243], off
	s_mov_b32 m0, s88
	s_nop 0
	global_load_lds_dwordx4 v[244:245], off
	s_waitcnt vmcnt(8)
	s_waitcnt lgkmcnt(0)
	s_barrier
; #define PG8_STAGE(bufoff, gbase, voff) do { _Pragma("unroll") for (int _i = 0; _i < 2; ++_i) \
;         __builtin_amdgcn_global_load_lds((const unsigned*)((const char*)(gbase) + (voff)[_i]), (LAS unsigned*)(lds + (bufoff) + ldsw + _i * 8192), 16, 0, 0); } while (0)
; #define PG8_LDA(dst, b, h) do { _Pragma("unroll") for (int m = 0; m < 4; ++m) _Pragma("unroll") for (int k = 0; k < 2; ++k) dst[m][k] = *(const LAS bf16x8*)(lds + PG8_SA(b, h) + aoff + m * 2048 + k * 1024); } while (0)
; #define PG8_LDB(dst, b, h) do { _Pragma("unroll") for (int n = 0; n < 2; ++n) _Pragma("unroll") for (int k = 0; k < 2; ++k) dst[n][k] = *(const LAS bf16x8*)(lds + PG8_SB(b, h) + boff + n * 2048 + k * 1024); } while (0)
; #define PG8_MMA(ai, bj, At, Bt) do { __builtin_amdgcn_s_setprio(1); _Pragma("unroll") for (int m = 0; m < 4; ++m) _Pragma("unroll") for (int n = 0; n < 2; ++n) _Pragma("unroll") for (int k = 0; k < 2; ++k) \
;         acc[ai][bj][m][n] = __builtin_amdgcn_mfma_f32_16x16x32_bf16(Bt[n][k], At[m][k], acc[ai][bj][m][n], 0, 0, 0); __builtin_amdgcn_s_setprio(0); } while (0)
; #define PG8_WAIT_V(n) asm volatile("s_waitcnt vmcnt(" #n ")" ::: "memory")
; #define PG8_WAIT_L(n) asm volatile("s_waitcnt lgkmcnt(" #n ")" ::: "memory")
; #define PG8_BAR __builtin_amdgcn_s_barrier()
; #define PG8_SCHED __builtin_amdgcn_sched_barrier(0)
; __device__ __forceinline__ void gemm_phase(const int tid, LAS unsigned char* lds, const Gemm g, const StaticOrder& S, const int mode  , void* Cout, const int ldc, float* rvs, const float* rbs, const float* rbs_tail) {
;     ...
;             PG8_WAIT_V(8); PG8_WAIT_L(0); PG8_BAR; PG8_MMA(0, 0, At, B0); PG8_MMA(0, 1, At, B1); PG8_BAR; PG8_SCHED;
;             PG8_LDA(At, 0, 1); PG8_STAGE(PG8_SB(0, 0), b2, voffB); PG8_STAGE(PG8_SB(0, 1), b2 + hstepB, voffB); PG8_STAGE(PG8_SA(0, 0), a2, voffA);
;             PG8_WAIT_V(8); PG8_WAIT_L(0); PG8_BAR; PG8_MMA(1, 0, At, B0); PG8_MMA(1, 1, At, B1); PG8_BAR; PG8_SCHED;
;             PG8_LDB(B0, 1, 0); PG8_LDB(B1, 1, 1); PG8_SCHED; PG8_LDA(At, 1, 0); PG8_STAGE(PG8_SA(0, 1), a2 + hstepA, voffA);
;             PG8_WAIT_V(8); PG8_WAIT_L(0); PG8_BAR; PG8_MMA(0, 0, At, B0); PG8_MMA(0, 1, At, B1); PG8_BAR; PG8_SCHED;
	s_setprio 1
	s_waitcnt lgkmcnt(0)
	v_mfma_f32_16x16x32_bf16 v[60:63], v[142:145], v[188:191], 0
	v_mfma_f32_16x16x32_bf16 v[56:59], v[154:157], v[188:191], 0
	v_mfma_f32_16x16x32_bf16 v[52:55], v[142:145], v[216:219], 0
	v_mfma_f32_16x16x32_bf16 v[48:51], v[154:157], v[216:219], 0
	v_mfma_f32_16x16x32_bf16 v[36:39], v[142:145], v[224:227], 0
	v_mfma_f32_16x16x32_bf16 v[32:35], v[154:157], v[224:227], 0
	v_mfma_f32_16x16x32_bf16 v[20:23], v[142:145], v[232:235], 0
	v_mfma_f32_16x16x32_bf16 v[16:19], v[154:157], v[232:235], 0
	v_mfma_f32_16x16x32_bf16 v[60:63], v[150:153], v[212:215], v[60:63]
	v_mfma_f32_16x16x32_bf16 v[56:59], v[168:171], v[212:215], v[56:59]
	v_mfma_f32_16x16x32_bf16 v[52:55], v[150:153], v[220:223], v[52:55]
	v_mfma_f32_16x16x32_bf16 v[48:51], v[168:171], v[220:223], v[48:51]
	v_mfma_f32_16x16x32_bf16 v[36:39], v[150:153], v[228:231], v[36:39]
	v_mfma_f32_16x16x32_bf16 v[32:35], v[168:171], v[228:231], v[32:35]
	v_mfma_f32_16x16x32_bf16 v[20:23], v[150:153], v[236:239], v[20:23]
	v_mfma_f32_16x16x32_bf16 v[16:19], v[168:171], v[236:239], v[16:19]
	s_setprio 0
	s_setprio 1
	v_mfma_f32_16x16x32_bf16 v[44:47], v[172:175], v[188:191], 0
	v_mfma_f32_16x16x32_bf16 v[40:43], v[180:183], v[188:191], 0
	v_mfma_f32_16x16x32_bf16 v[28:31], v[172:175], v[216:219], 0
	v_mfma_f32_16x16x32_bf16 v[24:27], v[180:183], v[216:219], 0
	v_mfma_f32_16x16x32_bf16 v[12:15], v[172:175], v[224:227], 0
	v_mfma_f32_16x16x32_bf16 v[8:11], v[180:183], v[224:227], 0
	v_mfma_f32_16x16x32_bf16 v[4:7], v[172:175], v[232:235], 0
	v_mfma_f32_16x16x32_bf16 v[0:3], v[180:183], v[232:235], 0
	v_mfma_f32_16x16x32_bf16 v[44:47], v[176:179], v[212:215], v[44:47]
	v_mfma_f32_16x16x32_bf16 v[40:43], v[184:187], v[212:215], v[40:43]
	v_mfma_f32_16x16x32_bf16 v[28:31], v[176:179], v[220:223], v[28:31]
	v_mfma_f32_16x16x32_bf16 v[24:27], v[184:187], v[220:223], v[24:27]
	v_mfma_f32_16x16x32_bf16 v[12:15], v[176:179], v[228:231], v[12:15]
	v_mfma_f32_16x16x32_bf16 v[8:11], v[184:187], v[228:231], v[8:11]
	v_mfma_f32_16x16x32_bf16 v[4:7], v[176:179], v[236:239], v[4:7]
	v_mfma_f32_16x16x32_bf16 v[0:3], v[184:187], v[236:239], v[0:3]
	s_setprio 0
	s_barrier
	s_add_i32 s68, 0, 0x18000
	v_add_u32_e32 v165, s68, v147
	s_add_i32 s73, 0, 0x1c000
	ds_read_b128 v[142:145], v165
	ds_read_b128 v[150:153], v165 offset:1024
	ds_read_b128 v[154:157], v165 offset:2048
	ds_read_b128 v[168:171], v165 offset:3072
	v_add_u32_e32 v165, s73, v147
	ds_read_b128 v[172:175], v165
	ds_read_b128 v[176:179], v165 offset:1024
	ds_read_b128 v[180:183], v165 offset:2048
	ds_read_b128 v[184:187], v165 offset:3072
	s_add_u32 s62, s62, s46
	s_addc_u32 s63, s63, 0
	s_mov_b32 m0, s89
	v_lshl_add_u64 v[246:247], s[62:63], 0, v[128:129]
	ds_read_b128 v[188:191], v149 offset:32768
	ds_read_b128 v[212:215], v149 offset:33792
	ds_read_b128 v[216:219], v149 offset:34816
	ds_read_b128 v[220:223], v149 offset:35840
	ds_read_b128 v[224:227], v149 offset:36864
	ds_read_b128 v[228:231], v149 offset:37888
	ds_read_b128 v[232:235], v149 offset:38912
	ds_read_b128 v[236:239], v149 offset:39936
	global_load_lds_dwordx4 v[246:247], off
	v_lshl_add_u64 v[246:247], s[62:63], 0, v[130:131]
	s_mov_b32 m0, s90
	s_nop 0
	global_load_lds_dwordx4 v[246:247], off
	s_waitcnt vmcnt(8)
	s_waitcnt lgkmcnt(0)
	s_barrier
	s_setprio 1
	s_waitcnt lgkmcnt(0)
	v_mfma_f32_16x16x32_bf16 v[124:127], v[142:145], v[188:191], v[124:127]
	v_mfma_f32_16x16x32_bf16 v[120:123], v[154:157], v[188:191], v[120:123]
	v_mfma_f32_16x16x32_bf16 v[116:119], v[142:145], v[216:219], v[116:119]
	v_mfma_f32_16x16x32_bf16 v[112:115], v[154:157], v[216:219], v[112:115]
	v_mfma_f32_16x16x32_bf16 v[104:107], v[142:145], v[224:227], v[104:107]
	v_mfma_f32_16x16x32_bf16 v[96:99], v[154:157], v[224:227], v[96:99]
	v_mfma_f32_16x16x32_bf16 v[88:91], v[142:145], v[232:235], v[88:91]
	v_mfma_f32_16x16x32_bf16 v[80:83], v[154:157], v[232:235], v[80:83]
	v_mfma_f32_16x16x32_bf16 v[124:127], v[150:153], v[212:215], v[124:127]
	v_mfma_f32_16x16x32_bf16 v[120:123], v[168:171], v[212:215], v[120:123]
	v_mfma_f32_16x16x32_bf16 v[116:119], v[150:153], v[220:223], v[116:119]
	v_mfma_f32_16x16x32_bf16 v[112:115], v[168:171], v[220:223], v[112:115]
	v_mfma_f32_16x16x32_bf16 v[104:107], v[150:153], v[228:231], v[104:107]
	v_mfma_f32_16x16x32_bf16 v[96:99], v[168:171], v[228:231], v[96:99]
	v_mfma_f32_16x16x32_bf16 v[88:91], v[150:153], v[236:239], v[88:91]
	v_mfma_f32_16x16x32_bf16 v[80:83], v[168:171], v[236:239], v[80:83]
	s_setprio 0
	s_setprio 1
	v_mfma_f32_16x16x32_bf16 v[108:111], v[172:175], v[188:191], v[108:111]
	v_mfma_f32_16x16x32_bf16 v[100:103], v[180:183], v[188:191], v[100:103]
	v_mfma_f32_16x16x32_bf16 v[92:95], v[172:175], v[216:219], v[92:95]
	v_mfma_f32_16x16x32_bf16 v[84:87], v[180:183], v[216:219], v[84:87]
	v_mfma_f32_16x16x32_bf16 v[76:79], v[172:175], v[224:227], v[76:79]
	v_mfma_f32_16x16x32_bf16 v[72:75], v[180:183], v[224:227], v[72:75]
	v_mfma_f32_16x16x32_bf16 v[68:71], v[172:175], v[232:235], v[68:71]
	v_mfma_f32_16x16x32_bf16 v[64:67], v[180:183], v[232:235], v[64:67]
	v_mfma_f32_16x16x32_bf16 v[108:111], v[176:179], v[212:215], v[108:111]
	v_mfma_f32_16x16x32_bf16 v[100:103], v[184:187], v[212:215], v[100:103]
	v_mfma_f32_16x16x32_bf16 v[92:95], v[176:179], v[220:223], v[92:95]
	v_mfma_f32_16x16x32_bf16 v[84:87], v[184:187], v[220:223], v[84:87]
	v_mfma_f32_16x16x32_bf16 v[76:79], v[176:179], v[228:231], v[76:79]
	v_mfma_f32_16x16x32_bf16 v[72:75], v[184:187], v[228:231], v[72:75]
	v_mfma_f32_16x16x32_bf16 v[68:71], v[176:179], v[236:239], v[68:71]
	v_mfma_f32_16x16x32_bf16 v[64:67], v[184:187], v[236:239], v[64:67]
	s_setprio 0
	s_barrier
; #define PG8_STAGE(bufoff, gbase, voff) do { _Pragma("unroll") for (int _i = 0; _i < 2; ++_i) \
;         __builtin_amdgcn_global_load_lds((const unsigned*)((const char*)(gbase) + (voff)[_i]), (LAS unsigned*)(lds + (bufoff) + ldsw + _i * 8192), 16, 0, 0); } while (0)
; #define PG8_LDA(dst, b, h) do { _Pragma("unroll") for (int m = 0; m < 4; ++m) _Pragma("unroll") for (int k = 0; k < 2; ++k) dst[m][k] = *(const LAS bf16x8*)(lds + PG8_SA(b, h) + aoff + m * 2048 + k * 1024); } while (0)
; #define PG8_MMA(ai, bj, At, Bt) do { __builtin_amdgcn_s_setprio(1); _Pragma("unroll") for (int m = 0; m < 4; ++m) _Pragma("unroll") for (int n = 0; n < 2; ++n) _Pragma("unroll") for (int k = 0; k < 2; ++k) \
;         acc[ai][bj][m][n] = __builtin_amdgcn_mfma_f32_16x16x32_bf16(Bt[n][k], At[m][k], acc[ai][bj][m][n], 0, 0, 0); __builtin_amdgcn_s_setprio(0); } while (0)
; #define PG8_WAIT_V(n) asm volatile("s_waitcnt vmcnt(" #n ")" ::: "memory")
; #define PG8_WAIT_L(n) asm volatile("s_waitcnt lgkmcnt(" #n ")" ::: "memory")
; #define PG8_BAR __builtin_amdgcn_s_barrier()
; #define PG8_SCHED __builtin_amdgcn_sched_barrier(0)
; __device__ __forceinline__ void gemm_phase(const int tid, LAS unsigned char* lds, const Gemm g, const StaticOrder& S, const int mode  , void* Cout, const int ldc, float* rvs, const float* rbs, const float* rbs_tail) {
;     ...
;             PG8_WAIT_V(8); PG8_WAIT_L(0); PG8_BAR; PG8_MMA(0, 0, At, B0); PG8_MMA(0, 1, At, B1); PG8_BAR; PG8_SCHED;
;             PG8_LDA(At, 1, 1); PG8_STAGE(PG8_SB(1, 0), b3, voffB); PG8_STAGE(PG8_SB(1, 1), b3 + hstepB, voffB); PG8_STAGE(PG8_SA(1, 0), a3, voffA);
;             PG8_WAIT_V(8); PG8_WAIT_L(0); PG8_BAR; PG8_MMA(1, 0, At, B0); PG8_MMA(1, 1, At, B1); PG8_BAR; PG8_SCHED;
;         }
	s_add_i32 s62, s68, s70
	v_lshl_add_u64 v[158:159], v[158:159], 0, s[36:37]
	s_mov_b32 m0, s62
	ds_read_b128 v[188:191], v149 offset:49152
	ds_read_b128 v[212:215], v149 offset:50176
	ds_read_b128 v[216:219], v149 offset:51200
	ds_read_b128 v[220:223], v149 offset:52224
	ds_read_b128 v[224:227], v149 offset:53248
	ds_read_b128 v[228:231], v149 offset:54272
	ds_read_b128 v[232:235], v149 offset:55296
	ds_read_b128 v[236:239], v149 offset:56320
	global_load_lds_dwordx4 v[158:159], off
	v_lshl_add_u64 v[158:159], v[192:193], 0, s[36:37]
	s_add_i32 m0, s62, 0x2000
	s_add_i32 s62, s73, s70
	global_load_lds_dwordx4 v[158:159], off
	v_lshl_add_u64 v[158:159], v[194:195], 0, s[36:37]
	s_mov_b32 m0, s62
	s_nop 0
	global_load_lds_dwordx4 v[158:159], off
	v_lshl_add_u64 v[158:159], v[240:241], 0, s[36:37]
	s_add_i32 m0, s62, 0x2000
	s_nop 0
	global_load_lds_dwordx4 v[158:159], off
	v_lshl_add_u64 v[158:159], v[242:243], 0, s[36:37]
	s_mov_b32 m0, s91
	s_nop 0
	global_load_lds_dwordx4 v[158:159], off
	v_lshl_add_u64 v[158:159], v[244:245], 0, s[36:37]
	s_mov_b32 m0, s16
	s_nop 0
	global_load_lds_dwordx4 v[158:159], off
	s_waitcnt vmcnt(8)
	s_waitcnt lgkmcnt(0)
	s_barrier
	s_setprio 1
	s_waitcnt lgkmcnt(0)
	v_mfma_f32_16x16x32_bf16 v[60:63], v[142:145], v[188:191], v[60:63]
	v_mfma_f32_16x16x32_bf16 v[56:59], v[154:157], v[188:191], v[56:59]
	v_mfma_f32_16x16x32_bf16 v[52:55], v[142:145], v[216:219], v[52:55]
	v_mfma_f32_16x16x32_bf16 v[48:51], v[154:157], v[216:219], v[48:51]
	v_mfma_f32_16x16x32_bf16 v[36:39], v[142:145], v[224:227], v[36:39]
	v_mfma_f32_16x16x32_bf16 v[32:35], v[154:157], v[224:227], v[32:35]
	v_mfma_f32_16x16x32_bf16 v[20:23], v[142:145], v[232:235], v[20:23]
	v_mfma_f32_16x16x32_bf16 v[16:19], v[154:157], v[232:235], v[16:19]
	v_mfma_f32_16x16x32_bf16 v[60:63], v[150:153], v[212:215], v[60:63]
	v_mfma_f32_16x16x32_bf16 v[56:59], v[168:171], v[212:215], v[56:59]
	v_mfma_f32_16x16x32_bf16 v[52:55], v[150:153], v[220:223], v[52:55]
	v_mfma_f32_16x16x32_bf16 v[48:51], v[168:171], v[220:223], v[48:51]
	v_mfma_f32_16x16x32_bf16 v[36:39], v[150:153], v[228:231], v[36:39]
	v_mfma_f32_16x16x32_bf16 v[32:35], v[168:171], v[228:231], v[32:35]
	v_mfma_f32_16x16x32_bf16 v[20:23], v[150:153], v[236:239], v[20:23]
	v_mfma_f32_16x16x32_bf16 v[16:19], v[168:171], v[236:239], v[16:19]
	s_setprio 0
	s_setprio 1
	v_mfma_f32_16x16x32_bf16 v[44:47], v[172:175], v[188:191], v[44:47]
	v_mfma_f32_16x16x32_bf16 v[40:43], v[180:183], v[188:191], v[40:43]
	v_mfma_f32_16x16x32_bf16 v[28:31], v[172:175], v[216:219], v[28:31]
	v_mfma_f32_16x16x32_bf16 v[24:27], v[180:183], v[216:219], v[24:27]
	v_mfma_f32_16x16x32_bf16 v[12:15], v[172:175], v[224:227], v[12:15]
	v_mfma_f32_16x16x32_bf16 v[8:11], v[180:183], v[224:227], v[8:11]
	v_mfma_f32_16x16x32_bf16 v[4:7], v[172:175], v[232:235], v[4:7]
	v_mfma_f32_16x16x32_bf16 v[0:3], v[180:183], v[232:235], v[0:3]
	v_mfma_f32_16x16x32_bf16 v[44:47], v[176:179], v[212:215], v[44:47]
	v_mfma_f32_16x16x32_bf16 v[40:43], v[184:187], v[212:215], v[40:43]
	v_mfma_f32_16x16x32_bf16 v[28:31], v[176:179], v[220:223], v[28:31]
	v_mfma_f32_16x16x32_bf16 v[24:27], v[184:187], v[220:223], v[24:27]
	v_mfma_f32_16x16x32_bf16 v[12:15], v[176:179], v[228:231], v[12:15]
	v_mfma_f32_16x16x32_bf16 v[8:11], v[184:187], v[228:231], v[8:11]
	v_mfma_f32_16x16x32_bf16 v[4:7], v[176:179], v[236:239], v[4:7]
	v_mfma_f32_16x16x32_bf16 v[0:3], v[184:187], v[236:239], v[0:3]
	s_setprio 0
	s_barrier
	s_add_u32 s60, s60, 0x100
	s_addc_u32 s61, s61, 0
	s_add_u32 s45, s45, 0x100
	s_addc_u32 s53, s53, 0
	s_cmp_ge_u32 s72, s3
	s_mov_b32 s68, s72
	s_cbranch_scc0 .LBB0_231
	s_branch .Lgemm_k_done

; #define PG8_BAR __builtin_amdgcn_s_barrier()
; __device__ __forceinline__ void gemm_phase(const int tid, LAS unsigned char* lds, const Gemm g, const StaticOrder& S, const int mode  , void* Cout, const int ldc, float* rvs, const float* rbs, const float* rbs_tail) {
;     ...
;         }
;         if (wr == 0) PG8_BAR;
.Lgemm_k_done:
	s_and_b64 vcc, exec, s[50:51]
	s_cbranch_vccz .LBB0_234
	s_barrier
